# accumulator zero-init at each tile top uses v_pk_mov_b32 (2 regs per issue) instead of 127 v_mov_b32, all 8 gemm phases
# speedup vs baseline: 1.0057x; 1.0057x over previous
; template <class Epi>
; __device__ __forceinline__ void gemm_phase(LAS unsigned char* lds, const Gemm g, const StaticOrder& S, const Epi& E) {
;     ...
;         const bool has_next = S.next(ui + 1, nxt);
;         const char* nA = has_next ? (const char*)g.A + (size_t)nxt.pm * tstepA : cA; const char* nB = has_next ? (const char*)g.Bt + (size_t)nxt.pn * tstepB : cB;
;     ...
;         for (int a = 0; a < 2; ++a)
; #pragma unroll
;             for (int b = 0; b < 2; ++b)
; #pragma unroll
;                 for (int m = 0; m < 4; ++m)
; #pragma unroll
;                     for (int n = 0; n < 2; ++n) acc[a][b][m][n] = (f32x4){0.f, 0.f, 0.f, 0.f};
;         cur = nxt; cA = nA; cB = nB; ++ui;
;     __device__ __forceinline__ void operator()(const Acc& acc, const Unit& u, int wr, int wc, int fr, int fq) const {
;         float ssv[2][4];
; #pragma unroll
;         for (int ai = 0; ai < 2; ++ai)
; #pragma unroll
;             for (int m = 0; m < 4; ++m) ssv[ai][m] = ss[u.pm * 256 + ai * 128 + wr * 64 + m * 16 + fr];
.LBB0_451:
	s_ashr_i32 s15, s14, 31
	s_lshl_b64 s[16:17], s[14:15], 19
	v_readlane_b32 s18, v254, 49
	v_readlane_b32 s19, v254, 50
	s_add_u32 s16, s18, s16
	s_addc_u32 s17, s19, s17
	s_and_b64 s[18:19], s[2:3], exec
	s_cselect_b32 s15, s17, s29
	s_cselect_b32 s57, s16, s28
	s_ashr_i32 s13, s12, 31
	s_lshl_b64 s[18:19], s[12:13], 19
	v_readlane_b32 s38, v254, 35
	v_readlane_b32 s39, v254, 36
	s_add_u32 s18, s38, s18
	s_addc_u32 s19, s39, s19
	s_and_b64 s[38:39], s[2:3], exec
	s_cselect_b32 s13, s19, s31
	s_cselect_b32 s58, s18, s30
	s_add_u32 s28, s28, 0x40080
	s_addc_u32 s29, s29, 0
	s_add_u32 s59, s30, 0x100
	v_mov_b32_e32 v0, 0
	s_addc_u32 s60, s31, 0
	s_mov_b32 s61, -2
	v_mov_b32_e32 v1, 0
	v_pk_mov_b32 v[2:3], v[0:1], v[0:1]
	v_pk_mov_b32 v[4:5], v[0:1], v[0:1]
	v_pk_mov_b32 v[6:7], v[0:1], v[0:1]
	v_pk_mov_b32 v[8:9], v[0:1], v[0:1]
	v_pk_mov_b32 v[10:11], v[0:1], v[0:1]
	v_pk_mov_b32 v[12:13], v[0:1], v[0:1]
	v_pk_mov_b32 v[14:15], v[0:1], v[0:1]
	v_pk_mov_b32 v[16:17], v[0:1], v[0:1]
	v_pk_mov_b32 v[18:19], v[0:1], v[0:1]
	v_pk_mov_b32 v[20:21], v[0:1], v[0:1]
	v_pk_mov_b32 v[22:23], v[0:1], v[0:1]
	v_pk_mov_b32 v[24:25], v[0:1], v[0:1]
	v_pk_mov_b32 v[26:27], v[0:1], v[0:1]
	v_pk_mov_b32 v[28:29], v[0:1], v[0:1]
	v_pk_mov_b32 v[30:31], v[0:1], v[0:1]
	v_pk_mov_b32 v[32:33], v[0:1], v[0:1]
	v_pk_mov_b32 v[34:35], v[0:1], v[0:1]
	v_pk_mov_b32 v[36:37], v[0:1], v[0:1]
	v_pk_mov_b32 v[38:39], v[0:1], v[0:1]
	v_pk_mov_b32 v[40:41], v[0:1], v[0:1]
	v_pk_mov_b32 v[42:43], v[0:1], v[0:1]
	v_pk_mov_b32 v[44:45], v[0:1], v[0:1]
	v_pk_mov_b32 v[46:47], v[0:1], v[0:1]
	v_pk_mov_b32 v[48:49], v[0:1], v[0:1]
	v_pk_mov_b32 v[50:51], v[0:1], v[0:1]
	v_pk_mov_b32 v[52:53], v[0:1], v[0:1]
	v_pk_mov_b32 v[54:55], v[0:1], v[0:1]
	v_pk_mov_b32 v[56:57], v[0:1], v[0:1]
	v_pk_mov_b32 v[58:59], v[0:1], v[0:1]
	v_pk_mov_b32 v[60:61], v[0:1], v[0:1]
	v_pk_mov_b32 v[62:63], v[0:1], v[0:1]
	v_pk_mov_b32 v[64:65], v[0:1], v[0:1]
	v_pk_mov_b32 v[66:67], v[0:1], v[0:1]
	v_pk_mov_b32 v[68:69], v[0:1], v[0:1]
	v_pk_mov_b32 v[70:71], v[0:1], v[0:1]
	v_pk_mov_b32 v[72:73], v[0:1], v[0:1]
	v_pk_mov_b32 v[74:75], v[0:1], v[0:1]
	v_pk_mov_b32 v[76:77], v[0:1], v[0:1]
	v_pk_mov_b32 v[78:79], v[0:1], v[0:1]
	v_pk_mov_b32 v[80:81], v[0:1], v[0:1]
	v_pk_mov_b32 v[82:83], v[0:1], v[0:1]
	v_pk_mov_b32 v[84:85], v[0:1], v[0:1]
	v_pk_mov_b32 v[86:87], v[0:1], v[0:1]
	v_pk_mov_b32 v[88:89], v[0:1], v[0:1]
	v_pk_mov_b32 v[90:91], v[0:1], v[0:1]
	v_pk_mov_b32 v[92:93], v[0:1], v[0:1]
	v_pk_mov_b32 v[94:95], v[0:1], v[0:1]
	v_pk_mov_b32 v[96:97], v[0:1], v[0:1]
	v_pk_mov_b32 v[98:99], v[0:1], v[0:1]
	v_pk_mov_b32 v[100:101], v[0:1], v[0:1]
	v_pk_mov_b32 v[102:103], v[0:1], v[0:1]
	v_pk_mov_b32 v[104:105], v[0:1], v[0:1]
	v_pk_mov_b32 v[106:107], v[0:1], v[0:1]
	v_pk_mov_b32 v[108:109], v[0:1], v[0:1]
	v_pk_mov_b32 v[110:111], v[0:1], v[0:1]
	v_pk_mov_b32 v[112:113], v[0:1], v[0:1]
	v_pk_mov_b32 v[114:115], v[0:1], v[0:1]
	v_pk_mov_b32 v[116:117], v[0:1], v[0:1]
	v_pk_mov_b32 v[118:119], v[0:1], v[0:1]
	v_pk_mov_b32 v[120:121], v[0:1], v[0:1]
	v_pk_mov_b32 v[122:123], v[0:1], v[0:1]
	v_pk_mov_b32 v[124:125], v[0:1], v[0:1]
	v_pk_mov_b32 v[126:127], v[0:1], v[0:1]
	v_readlane_b32 s86, v254, 9
	v_readlane_b32 s87, v254, 10
	s_lshl_b32 s85, s0, 8
	s_add_i32 s85, s85, s46
	v_or_b32_e32 v250, s85, v144
	v_ashrrev_i32_e32 v251, 31, v250
	v_lshl_add_u64 v[252:253], v[250:251], 2, s[86:87]
	global_load_dword v235, v[252:253], off
	global_load_dword v236, v[252:253], off offset:64
	global_load_dword v237, v[252:253], off offset:128
	global_load_dword v238, v[252:253], off offset:192
	global_load_dword v239, v[252:253], off offset:512
	global_load_dword v240, v[252:253], off offset:576
	global_load_dword v241, v[252:253], off offset:640
	global_load_dword v242, v[252:253], off offset:704

; template <class Epi>
; __device__ __forceinline__ void gemm_phase(LAS unsigned char* lds, const Gemm g, const StaticOrder& S, const Epi& E) {
;     ...
;         for (int a = 0; a < 2; ++a)
; #pragma unroll
;             for (int b = 0; b < 2; ++b)
; #pragma unroll
;                 for (int m = 0; m < 4; ++m)
; #pragma unroll
;                     for (int n = 0; n < 2; ++n) acc[a][b][m][n] = (f32x4){0.f, 0.f, 0.f, 0.f};
;         cur = nxt; cA = nA; cB = nB; ++ui;
.LBB0_547:
	s_add_u32 s14, s0, 0x100
	s_addc_u32 s15, s1, 0
	s_add_u32 s0, s2, 0xc000
	v_mov_b32_e32 v0, 0
	s_addc_u32 s1, s3, 0
	s_mov_b32 s16, -2
	s_waitcnt lgkmcnt(0)
	v_mov_b32_e32 v1, 0
	v_pk_mov_b32 v[2:3], v[0:1], v[0:1]
	v_pk_mov_b32 v[4:5], v[0:1], v[0:1]
	v_pk_mov_b32 v[6:7], v[0:1], v[0:1]
	v_pk_mov_b32 v[8:9], v[0:1], v[0:1]
	v_pk_mov_b32 v[10:11], v[0:1], v[0:1]
	v_pk_mov_b32 v[12:13], v[0:1], v[0:1]
	v_pk_mov_b32 v[14:15], v[0:1], v[0:1]
	v_pk_mov_b32 v[16:17], v[0:1], v[0:1]
	v_pk_mov_b32 v[18:19], v[0:1], v[0:1]
	v_pk_mov_b32 v[20:21], v[0:1], v[0:1]
	v_pk_mov_b32 v[22:23], v[0:1], v[0:1]
	v_pk_mov_b32 v[24:25], v[0:1], v[0:1]
	v_pk_mov_b32 v[26:27], v[0:1], v[0:1]
	v_pk_mov_b32 v[28:29], v[0:1], v[0:1]
	v_pk_mov_b32 v[30:31], v[0:1], v[0:1]
	v_pk_mov_b32 v[32:33], v[0:1], v[0:1]
	v_pk_mov_b32 v[34:35], v[0:1], v[0:1]
	v_pk_mov_b32 v[36:37], v[0:1], v[0:1]
	v_pk_mov_b32 v[38:39], v[0:1], v[0:1]
	v_pk_mov_b32 v[40:41], v[0:1], v[0:1]
	v_pk_mov_b32 v[42:43], v[0:1], v[0:1]
	v_pk_mov_b32 v[44:45], v[0:1], v[0:1]
	v_pk_mov_b32 v[46:47], v[0:1], v[0:1]
	v_pk_mov_b32 v[48:49], v[0:1], v[0:1]
	v_pk_mov_b32 v[50:51], v[0:1], v[0:1]
	v_pk_mov_b32 v[52:53], v[0:1], v[0:1]
	v_pk_mov_b32 v[54:55], v[0:1], v[0:1]
	v_pk_mov_b32 v[56:57], v[0:1], v[0:1]
	v_pk_mov_b32 v[58:59], v[0:1], v[0:1]
	v_pk_mov_b32 v[60:61], v[0:1], v[0:1]
	v_pk_mov_b32 v[62:63], v[0:1], v[0:1]
	v_pk_mov_b32 v[64:65], v[0:1], v[0:1]
	v_pk_mov_b32 v[66:67], v[0:1], v[0:1]
	v_pk_mov_b32 v[68:69], v[0:1], v[0:1]
	v_pk_mov_b32 v[70:71], v[0:1], v[0:1]
	v_pk_mov_b32 v[72:73], v[0:1], v[0:1]
	v_pk_mov_b32 v[74:75], v[0:1], v[0:1]
	v_pk_mov_b32 v[76:77], v[0:1], v[0:1]
	v_pk_mov_b32 v[78:79], v[0:1], v[0:1]
	v_pk_mov_b32 v[80:81], v[0:1], v[0:1]
	v_pk_mov_b32 v[82:83], v[0:1], v[0:1]
	v_pk_mov_b32 v[84:85], v[0:1], v[0:1]
	v_pk_mov_b32 v[86:87], v[0:1], v[0:1]
	v_pk_mov_b32 v[88:89], v[0:1], v[0:1]
	v_pk_mov_b32 v[90:91], v[0:1], v[0:1]
	v_pk_mov_b32 v[92:93], v[0:1], v[0:1]
	v_pk_mov_b32 v[94:95], v[0:1], v[0:1]
	v_pk_mov_b32 v[96:97], v[0:1], v[0:1]
	v_pk_mov_b32 v[98:99], v[0:1], v[0:1]
	v_pk_mov_b32 v[100:101], v[0:1], v[0:1]
	v_pk_mov_b32 v[102:103], v[0:1], v[0:1]
	v_pk_mov_b32 v[104:105], v[0:1], v[0:1]
	v_pk_mov_b32 v[106:107], v[0:1], v[0:1]
	v_pk_mov_b32 v[108:109], v[0:1], v[0:1]
	v_pk_mov_b32 v[110:111], v[0:1], v[0:1]
	v_pk_mov_b32 v[112:113], v[0:1], v[0:1]
	v_pk_mov_b32 v[114:115], v[0:1], v[0:1]
	v_pk_mov_b32 v[116:117], v[0:1], v[0:1]
	v_pk_mov_b32 v[118:119], v[0:1], v[0:1]
	v_pk_mov_b32 v[120:121], v[0:1], v[0:1]
	v_pk_mov_b32 v[122:123], v[0:1], v[0:1]
	v_pk_mov_b32 v[124:125], v[0:1], v[0:1]
	v_pk_mov_b32 v[126:127], v[0:1], v[0:1]
	s_waitcnt vmcnt(0)

; template <class Epi>
; __device__ __forceinline__ void gemm_phase(LAS unsigned char* lds, const Gemm g, const StaticOrder& S, const Epi& E) {
;     ...
;         for (int a = 0; a < 2; ++a)
; #pragma unroll
;             for (int b = 0; b < 2; ++b)
; #pragma unroll
;                 for (int m = 0; m < 4; ++m)
; #pragma unroll
;                     for (int n = 0; n < 2; ++n) acc[a][b][m][n] = (f32x4){0.f, 0.f, 0.f, 0.f};
;         cur = nxt; cA = nA; cB = nB; ++ui;
;     __device__ __forceinline__ void operator()(const Acc& acc, const Unit& u, int wr, int wc, int fr, int fq) const {
;     ...
;                 const int row = u.pm * 256 + ai * 128 + wr * 64 + m * 16 + fr;
;                 const float rs = rsqrtf(ss1[row] * (1.0f / DM) + EPS);
.LBB0_686:
	s_ashr_i32 s49, s48, 31
	s_lshl_b64 s[14:15], s[48:49], 19
	v_readlane_b32 s16, v254, 49
	v_readlane_b32 s17, v254, 50
	s_add_u32 s52, s16, s14
	s_addc_u32 s53, s17, s15
	s_and_b64 s[14:15], s[8:9], exec
	s_cselect_b32 s1, s53, s11
	s_cselect_b32 s3, s52, s10
	s_ashr_i32 s47, s46, 31
	s_lshl_b64 s[14:15], s[46:47], 19
	s_add_u32 s54, s34, s14
	s_addc_u32 s55, s35, s15
	s_and_b64 s[14:15], s[8:9], exec
	s_cselect_b32 s16, s55, s13
	s_cselect_b32 s17, s54, s12
	s_add_u32 s10, s10, 0x40080
	s_addc_u32 s11, s11, 0
	s_add_u32 s18, s12, 0x100
	v_mov_b32_e32 v0, 0
	s_addc_u32 s19, s13, 0
	s_mov_b32 s30, -2
	v_mov_b32_e32 v1, 0
	v_pk_mov_b32 v[2:3], v[0:1], v[0:1]
	v_pk_mov_b32 v[4:5], v[0:1], v[0:1]
	v_pk_mov_b32 v[6:7], v[0:1], v[0:1]
	v_pk_mov_b32 v[8:9], v[0:1], v[0:1]
	v_pk_mov_b32 v[10:11], v[0:1], v[0:1]
	v_pk_mov_b32 v[12:13], v[0:1], v[0:1]
	v_pk_mov_b32 v[14:15], v[0:1], v[0:1]
	v_pk_mov_b32 v[16:17], v[0:1], v[0:1]
	v_pk_mov_b32 v[18:19], v[0:1], v[0:1]
	v_pk_mov_b32 v[20:21], v[0:1], v[0:1]
	v_pk_mov_b32 v[22:23], v[0:1], v[0:1]
	v_pk_mov_b32 v[24:25], v[0:1], v[0:1]
	v_pk_mov_b32 v[26:27], v[0:1], v[0:1]
	v_pk_mov_b32 v[28:29], v[0:1], v[0:1]
	v_pk_mov_b32 v[30:31], v[0:1], v[0:1]
	v_pk_mov_b32 v[32:33], v[0:1], v[0:1]
	v_pk_mov_b32 v[34:35], v[0:1], v[0:1]
	v_pk_mov_b32 v[36:37], v[0:1], v[0:1]
	v_pk_mov_b32 v[38:39], v[0:1], v[0:1]
	v_pk_mov_b32 v[40:41], v[0:1], v[0:1]
	v_pk_mov_b32 v[42:43], v[0:1], v[0:1]
	v_pk_mov_b32 v[44:45], v[0:1], v[0:1]
	v_pk_mov_b32 v[46:47], v[0:1], v[0:1]
	v_pk_mov_b32 v[48:49], v[0:1], v[0:1]
	v_pk_mov_b32 v[50:51], v[0:1], v[0:1]
	v_pk_mov_b32 v[52:53], v[0:1], v[0:1]
	v_pk_mov_b32 v[54:55], v[0:1], v[0:1]
	v_pk_mov_b32 v[56:57], v[0:1], v[0:1]
	v_pk_mov_b32 v[58:59], v[0:1], v[0:1]
	v_pk_mov_b32 v[60:61], v[0:1], v[0:1]
	v_pk_mov_b32 v[62:63], v[0:1], v[0:1]
	v_pk_mov_b32 v[64:65], v[0:1], v[0:1]
	v_pk_mov_b32 v[66:67], v[0:1], v[0:1]
	v_pk_mov_b32 v[68:69], v[0:1], v[0:1]
	v_pk_mov_b32 v[70:71], v[0:1], v[0:1]
	v_pk_mov_b32 v[72:73], v[0:1], v[0:1]
	v_pk_mov_b32 v[74:75], v[0:1], v[0:1]
	v_pk_mov_b32 v[76:77], v[0:1], v[0:1]
	v_pk_mov_b32 v[78:79], v[0:1], v[0:1]
	v_pk_mov_b32 v[80:81], v[0:1], v[0:1]
	v_pk_mov_b32 v[82:83], v[0:1], v[0:1]
	v_pk_mov_b32 v[84:85], v[0:1], v[0:1]
	v_pk_mov_b32 v[86:87], v[0:1], v[0:1]
	v_pk_mov_b32 v[88:89], v[0:1], v[0:1]
	v_pk_mov_b32 v[90:91], v[0:1], v[0:1]
	v_pk_mov_b32 v[92:93], v[0:1], v[0:1]
	v_pk_mov_b32 v[94:95], v[0:1], v[0:1]
	v_pk_mov_b32 v[96:97], v[0:1], v[0:1]
	v_pk_mov_b32 v[98:99], v[0:1], v[0:1]
	v_pk_mov_b32 v[100:101], v[0:1], v[0:1]
	v_pk_mov_b32 v[102:103], v[0:1], v[0:1]
	v_pk_mov_b32 v[104:105], v[0:1], v[0:1]
	v_pk_mov_b32 v[106:107], v[0:1], v[0:1]
	v_pk_mov_b32 v[108:109], v[0:1], v[0:1]
	v_pk_mov_b32 v[110:111], v[0:1], v[0:1]
	v_pk_mov_b32 v[112:113], v[0:1], v[0:1]
	v_pk_mov_b32 v[114:115], v[0:1], v[0:1]
	v_pk_mov_b32 v[116:117], v[0:1], v[0:1]
	v_pk_mov_b32 v[118:119], v[0:1], v[0:1]
	v_pk_mov_b32 v[120:121], v[0:1], v[0:1]
	v_pk_mov_b32 v[122:123], v[0:1], v[0:1]
	v_pk_mov_b32 v[124:125], v[0:1], v[0:1]
	v_pk_mov_b32 v[126:127], v[0:1], v[0:1]
	s_lshl_b32 s87, s2, 8
	s_add_i32 s87, s87, s61
	v_or_b32_e32 v250, s87, v145
	v_ashrrev_i32_e32 v251, 31, v250
	v_lshl_add_u64 v[252:253], v[250:251], 2, s[28:29]
	global_load_dword v238, v[252:253], off
	global_load_dword v239, v[252:253], off offset:64
	global_load_dword v240, v[252:253], off offset:128
	global_load_dword v241, v[252:253], off offset:192
	global_load_dword v242, v[252:253], off offset:512
	global_load_dword v246, v[252:253], off offset:576
	global_load_dword v247, v[252:253], off offset:640
	global_load_dword v248, v[252:253], off offset:704

; template <class Epi>
; __device__ __forceinline__ void gemm_phase(LAS unsigned char* lds, const Gemm g, const StaticOrder& S, const Epi& E) {
;     ...
;         for (int a = 0; a < 2; ++a)
; #pragma unroll
;             for (int b = 0; b < 2; ++b)
; #pragma unroll
;                 for (int m = 0; m < 4; ++m)
; #pragma unroll
;                     for (int n = 0; n < 2; ++n) acc[a][b][m][n] = (f32x4){0.f, 0.f, 0.f, 0.f};
;         cur = nxt; cA = nA; cB = nB; ++ui;
.LBB0_1459:
	s_ashr_i32 s13, s12, 31
	s_lshl_b64 s[16:17], s[12:13], 18
	v_readlane_b32 s22, v254, 37
	v_readlane_b32 s23, v254, 38
	s_add_u32 s16, s22, s16
	s_addc_u32 s17, s23, s17
	s_and_b64 s[6:7], s[6:7], exec
	s_cselect_b32 s13, s17, s21
	s_cselect_b32 s42, s16, s20
	s_add_u32 s43, s20, 0x100
	v_mov_b32_e32 v0, 0
	s_addc_u32 s44, s21, 0
	s_mov_b32 s45, -2
	v_mov_b32_e32 v1, 0
	v_pk_mov_b32 v[2:3], v[0:1], v[0:1]
	v_pk_mov_b32 v[4:5], v[0:1], v[0:1]
	v_pk_mov_b32 v[6:7], v[0:1], v[0:1]
	v_pk_mov_b32 v[8:9], v[0:1], v[0:1]
	v_pk_mov_b32 v[10:11], v[0:1], v[0:1]
	v_pk_mov_b32 v[12:13], v[0:1], v[0:1]
	v_pk_mov_b32 v[14:15], v[0:1], v[0:1]
	v_pk_mov_b32 v[16:17], v[0:1], v[0:1]
	v_pk_mov_b32 v[18:19], v[0:1], v[0:1]
	v_pk_mov_b32 v[20:21], v[0:1], v[0:1]
	v_pk_mov_b32 v[22:23], v[0:1], v[0:1]
	v_pk_mov_b32 v[24:25], v[0:1], v[0:1]
	v_pk_mov_b32 v[26:27], v[0:1], v[0:1]
	v_pk_mov_b32 v[28:29], v[0:1], v[0:1]
	v_pk_mov_b32 v[30:31], v[0:1], v[0:1]
	v_pk_mov_b32 v[32:33], v[0:1], v[0:1]
	v_pk_mov_b32 v[34:35], v[0:1], v[0:1]
	v_pk_mov_b32 v[36:37], v[0:1], v[0:1]
	v_pk_mov_b32 v[38:39], v[0:1], v[0:1]
	v_pk_mov_b32 v[40:41], v[0:1], v[0:1]
	v_pk_mov_b32 v[42:43], v[0:1], v[0:1]
	v_pk_mov_b32 v[44:45], v[0:1], v[0:1]
	v_pk_mov_b32 v[46:47], v[0:1], v[0:1]
	v_pk_mov_b32 v[48:49], v[0:1], v[0:1]
	v_pk_mov_b32 v[50:51], v[0:1], v[0:1]
	v_pk_mov_b32 v[52:53], v[0:1], v[0:1]
	v_pk_mov_b32 v[54:55], v[0:1], v[0:1]
	v_pk_mov_b32 v[56:57], v[0:1], v[0:1]
	v_pk_mov_b32 v[58:59], v[0:1], v[0:1]
	v_pk_mov_b32 v[60:61], v[0:1], v[0:1]
	v_pk_mov_b32 v[62:63], v[0:1], v[0:1]
	v_pk_mov_b32 v[64:65], v[0:1], v[0:1]
	v_pk_mov_b32 v[66:67], v[0:1], v[0:1]
	v_pk_mov_b32 v[68:69], v[0:1], v[0:1]
	v_pk_mov_b32 v[70:71], v[0:1], v[0:1]
	v_pk_mov_b32 v[72:73], v[0:1], v[0:1]
	v_pk_mov_b32 v[74:75], v[0:1], v[0:1]
	v_pk_mov_b32 v[76:77], v[0:1], v[0:1]
	v_pk_mov_b32 v[78:79], v[0:1], v[0:1]
	v_pk_mov_b32 v[80:81], v[0:1], v[0:1]
	v_pk_mov_b32 v[82:83], v[0:1], v[0:1]
	v_pk_mov_b32 v[84:85], v[0:1], v[0:1]
	v_pk_mov_b32 v[86:87], v[0:1], v[0:1]
	v_pk_mov_b32 v[88:89], v[0:1], v[0:1]
	v_pk_mov_b32 v[90:91], v[0:1], v[0:1]
	v_pk_mov_b32 v[92:93], v[0:1], v[0:1]
	v_pk_mov_b32 v[94:95], v[0:1], v[0:1]
	v_pk_mov_b32 v[96:97], v[0:1], v[0:1]
	v_pk_mov_b32 v[98:99], v[0:1], v[0:1]
	v_pk_mov_b32 v[100:101], v[0:1], v[0:1]
	v_pk_mov_b32 v[102:103], v[0:1], v[0:1]
	v_pk_mov_b32 v[104:105], v[0:1], v[0:1]
	v_pk_mov_b32 v[106:107], v[0:1], v[0:1]
	v_pk_mov_b32 v[108:109], v[0:1], v[0:1]
	v_pk_mov_b32 v[110:111], v[0:1], v[0:1]
	v_pk_mov_b32 v[112:113], v[0:1], v[0:1]
	v_pk_mov_b32 v[114:115], v[0:1], v[0:1]
	v_pk_mov_b32 v[116:117], v[0:1], v[0:1]
	v_pk_mov_b32 v[118:119], v[0:1], v[0:1]
	v_pk_mov_b32 v[120:121], v[0:1], v[0:1]
	v_pk_mov_b32 v[122:123], v[0:1], v[0:1]
	v_pk_mov_b32 v[124:125], v[0:1], v[0:1]
	v_pk_mov_b32 v[126:127], v[0:1], v[0:1]
	s_waitcnt vmcnt(0)

; template <class Epi>
; __device__ __forceinline__ void gemm_phase(LAS unsigned char* lds, const Gemm g, const StaticOrder& S, const Epi& E) {
;     ...
;         for (int a = 0; a < 2; ++a)
; #pragma unroll
;             for (int b = 0; b < 2; ++b)
; #pragma unroll
;                 for (int m = 0; m < 4; ++m)
; #pragma unroll
;                     for (int n = 0; n < 2; ++n) acc[a][b][m][n] = (f32x4){0.f, 0.f, 0.f, 0.f};
;         cur = nxt; cA = nA; cB = nB; ++ui;
.LBB0_1502:
	s_ashr_i32 s15, s14, 31
	s_lshl_b64 s[18:19], s[14:15], 20
	v_readlane_b32 s24, v254, 39
	v_readlane_b32 s25, v254, 40
	s_add_u32 s18, s24, s18
	s_addc_u32 s19, s25, s19
	s_and_b64 s[8:9], s[8:9], exec
	s_cselect_b32 s15, s19, s23
	s_cselect_b32 s47, s18, s22
	s_add_u32 s48, s22, 0x100
	v_mov_b32_e32 v0, 0
	s_addc_u32 s49, s23, 0
	s_mov_b32 s50, -2
	v_mov_b32_e32 v1, 0
	v_pk_mov_b32 v[2:3], v[0:1], v[0:1]
	v_pk_mov_b32 v[4:5], v[0:1], v[0:1]
	v_pk_mov_b32 v[6:7], v[0:1], v[0:1]
	v_pk_mov_b32 v[8:9], v[0:1], v[0:1]
	v_pk_mov_b32 v[10:11], v[0:1], v[0:1]
	v_pk_mov_b32 v[12:13], v[0:1], v[0:1]
	v_pk_mov_b32 v[14:15], v[0:1], v[0:1]
	v_pk_mov_b32 v[16:17], v[0:1], v[0:1]
	v_pk_mov_b32 v[18:19], v[0:1], v[0:1]
	v_pk_mov_b32 v[20:21], v[0:1], v[0:1]
	v_pk_mov_b32 v[22:23], v[0:1], v[0:1]
	v_pk_mov_b32 v[24:25], v[0:1], v[0:1]
	v_pk_mov_b32 v[26:27], v[0:1], v[0:1]
	v_pk_mov_b32 v[28:29], v[0:1], v[0:1]
	v_pk_mov_b32 v[30:31], v[0:1], v[0:1]
	v_pk_mov_b32 v[32:33], v[0:1], v[0:1]
	v_pk_mov_b32 v[34:35], v[0:1], v[0:1]
	v_pk_mov_b32 v[36:37], v[0:1], v[0:1]
	v_pk_mov_b32 v[38:39], v[0:1], v[0:1]
	v_pk_mov_b32 v[40:41], v[0:1], v[0:1]
	v_pk_mov_b32 v[42:43], v[0:1], v[0:1]
	v_pk_mov_b32 v[44:45], v[0:1], v[0:1]
	v_pk_mov_b32 v[46:47], v[0:1], v[0:1]
	v_pk_mov_b32 v[48:49], v[0:1], v[0:1]
	v_pk_mov_b32 v[50:51], v[0:1], v[0:1]
	v_pk_mov_b32 v[52:53], v[0:1], v[0:1]
	v_pk_mov_b32 v[54:55], v[0:1], v[0:1]
	v_pk_mov_b32 v[56:57], v[0:1], v[0:1]
	v_pk_mov_b32 v[58:59], v[0:1], v[0:1]
	v_pk_mov_b32 v[60:61], v[0:1], v[0:1]
	v_pk_mov_b32 v[62:63], v[0:1], v[0:1]
	v_pk_mov_b32 v[64:65], v[0:1], v[0:1]
	v_pk_mov_b32 v[66:67], v[0:1], v[0:1]
	v_pk_mov_b32 v[68:69], v[0:1], v[0:1]
	v_pk_mov_b32 v[70:71], v[0:1], v[0:1]
	v_pk_mov_b32 v[72:73], v[0:1], v[0:1]
	v_pk_mov_b32 v[74:75], v[0:1], v[0:1]
	v_pk_mov_b32 v[76:77], v[0:1], v[0:1]
	v_pk_mov_b32 v[78:79], v[0:1], v[0:1]
	v_pk_mov_b32 v[80:81], v[0:1], v[0:1]
	v_pk_mov_b32 v[82:83], v[0:1], v[0:1]
	v_pk_mov_b32 v[84:85], v[0:1], v[0:1]
	v_pk_mov_b32 v[86:87], v[0:1], v[0:1]
	v_pk_mov_b32 v[88:89], v[0:1], v[0:1]
	v_pk_mov_b32 v[90:91], v[0:1], v[0:1]
	v_pk_mov_b32 v[92:93], v[0:1], v[0:1]
	v_pk_mov_b32 v[94:95], v[0:1], v[0:1]
	v_pk_mov_b32 v[96:97], v[0:1], v[0:1]
	v_pk_mov_b32 v[98:99], v[0:1], v[0:1]
	v_pk_mov_b32 v[100:101], v[0:1], v[0:1]
	v_pk_mov_b32 v[102:103], v[0:1], v[0:1]
	v_pk_mov_b32 v[104:105], v[0:1], v[0:1]
	v_pk_mov_b32 v[106:107], v[0:1], v[0:1]
	v_pk_mov_b32 v[108:109], v[0:1], v[0:1]
	v_pk_mov_b32 v[110:111], v[0:1], v[0:1]
	v_pk_mov_b32 v[112:113], v[0:1], v[0:1]
	v_pk_mov_b32 v[114:115], v[0:1], v[0:1]
	v_pk_mov_b32 v[116:117], v[0:1], v[0:1]
	v_pk_mov_b32 v[118:119], v[0:1], v[0:1]
	v_pk_mov_b32 v[120:121], v[0:1], v[0:1]
	v_pk_mov_b32 v[122:123], v[0:1], v[0:1]
	v_pk_mov_b32 v[124:125], v[0:1], v[0:1]
	v_pk_mov_b32 v[126:127], v[0:1], v[0:1]
	s_waitcnt vmcnt(0)

; template <class Epi>
; __device__ __forceinline__ void gemm_phase(LAS unsigned char* lds, const Gemm g, const StaticOrder& S, const Epi& E) {
;     ...
;         for (int a = 0; a < 2; ++a)
; #pragma unroll
;             for (int b = 0; b < 2; ++b)
; #pragma unroll
;                 for (int m = 0; m < 4; ++m)
; #pragma unroll
;                     for (int n = 0; n < 2; ++n) acc[a][b][m][n] = (f32x4){0.f, 0.f, 0.f, 0.f};
;         cur = nxt; cA = nA; cB = nB; ++ui;
.LBB0_1597:
	s_ashr_i32 s29, s28, 31
	s_lshl_b64 s[14:15], s[28:29], 19
	v_readlane_b32 s30, v254, 49
	v_readlane_b32 s31, v254, 50
	s_add_u32 s30, s30, s14
	s_addc_u32 s31, s31, s15
	s_and_b64 s[14:15], s[8:9], exec
	s_cselect_b32 s1, s31, s11
	s_cselect_b32 s29, s30, s10
	s_ashr_i32 s27, s26, 31
	s_lshl_b64 s[14:15], s[26:27], 19
	v_readlane_b32 s34, v254, 41
	v_readlane_b32 s35, v254, 42
	s_add_u32 s34, s34, s14
	s_addc_u32 s35, s35, s15
	s_and_b64 s[14:15], s[8:9], exec
	s_cselect_b32 s27, s35, s13
	s_cselect_b32 s51, s34, s12
	s_add_u32 s10, s10, 0x40080
	s_addc_u32 s11, s11, 0
	s_add_u32 s52, s12, 0x100
	v_mov_b32_e32 v0, 0
	s_addc_u32 s53, s13, 0
	s_mov_b32 s54, -2
	s_waitcnt lgkmcnt(0)
	v_mov_b32_e32 v1, 0
	v_pk_mov_b32 v[2:3], v[0:1], v[0:1]
	v_pk_mov_b32 v[4:5], v[0:1], v[0:1]
	v_pk_mov_b32 v[6:7], v[0:1], v[0:1]
	v_pk_mov_b32 v[8:9], v[0:1], v[0:1]
	v_pk_mov_b32 v[10:11], v[0:1], v[0:1]
	v_pk_mov_b32 v[12:13], v[0:1], v[0:1]
	v_pk_mov_b32 v[14:15], v[0:1], v[0:1]
	v_pk_mov_b32 v[16:17], v[0:1], v[0:1]
	v_pk_mov_b32 v[18:19], v[0:1], v[0:1]
	v_pk_mov_b32 v[20:21], v[0:1], v[0:1]
	v_pk_mov_b32 v[22:23], v[0:1], v[0:1]
	v_pk_mov_b32 v[24:25], v[0:1], v[0:1]
	v_pk_mov_b32 v[26:27], v[0:1], v[0:1]
	v_pk_mov_b32 v[28:29], v[0:1], v[0:1]
	v_pk_mov_b32 v[30:31], v[0:1], v[0:1]
	v_pk_mov_b32 v[32:33], v[0:1], v[0:1]
	v_pk_mov_b32 v[34:35], v[0:1], v[0:1]
	v_pk_mov_b32 v[36:37], v[0:1], v[0:1]
	v_pk_mov_b32 v[38:39], v[0:1], v[0:1]
	v_pk_mov_b32 v[40:41], v[0:1], v[0:1]
	v_pk_mov_b32 v[42:43], v[0:1], v[0:1]
	v_pk_mov_b32 v[44:45], v[0:1], v[0:1]
	v_pk_mov_b32 v[46:47], v[0:1], v[0:1]
	v_pk_mov_b32 v[48:49], v[0:1], v[0:1]
	v_pk_mov_b32 v[50:51], v[0:1], v[0:1]
	v_pk_mov_b32 v[52:53], v[0:1], v[0:1]
	v_pk_mov_b32 v[54:55], v[0:1], v[0:1]
	v_pk_mov_b32 v[56:57], v[0:1], v[0:1]
	v_pk_mov_b32 v[58:59], v[0:1], v[0:1]
	v_pk_mov_b32 v[60:61], v[0:1], v[0:1]
	v_pk_mov_b32 v[62:63], v[0:1], v[0:1]
	v_pk_mov_b32 v[64:65], v[0:1], v[0:1]
	v_pk_mov_b32 v[66:67], v[0:1], v[0:1]
	v_pk_mov_b32 v[68:69], v[0:1], v[0:1]
	v_pk_mov_b32 v[70:71], v[0:1], v[0:1]
	v_pk_mov_b32 v[72:73], v[0:1], v[0:1]
	v_pk_mov_b32 v[74:75], v[0:1], v[0:1]
	v_pk_mov_b32 v[76:77], v[0:1], v[0:1]
	v_pk_mov_b32 v[78:79], v[0:1], v[0:1]
	v_pk_mov_b32 v[80:81], v[0:1], v[0:1]
	v_pk_mov_b32 v[82:83], v[0:1], v[0:1]
	v_pk_mov_b32 v[84:85], v[0:1], v[0:1]
	v_pk_mov_b32 v[86:87], v[0:1], v[0:1]
	v_pk_mov_b32 v[88:89], v[0:1], v[0:1]
	v_pk_mov_b32 v[90:91], v[0:1], v[0:1]
	v_pk_mov_b32 v[92:93], v[0:1], v[0:1]
	v_pk_mov_b32 v[94:95], v[0:1], v[0:1]
	v_pk_mov_b32 v[96:97], v[0:1], v[0:1]
	v_pk_mov_b32 v[98:99], v[0:1], v[0:1]
	v_pk_mov_b32 v[100:101], v[0:1], v[0:1]
	v_pk_mov_b32 v[102:103], v[0:1], v[0:1]
	v_pk_mov_b32 v[104:105], v[0:1], v[0:1]
	v_pk_mov_b32 v[106:107], v[0:1], v[0:1]
	v_pk_mov_b32 v[108:109], v[0:1], v[0:1]
	v_pk_mov_b32 v[110:111], v[0:1], v[0:1]
	v_pk_mov_b32 v[112:113], v[0:1], v[0:1]
	v_pk_mov_b32 v[114:115], v[0:1], v[0:1]
	v_pk_mov_b32 v[116:117], v[0:1], v[0:1]
	v_pk_mov_b32 v[118:119], v[0:1], v[0:1]
	v_pk_mov_b32 v[120:121], v[0:1], v[0:1]
	v_pk_mov_b32 v[122:123], v[0:1], v[0:1]
	v_pk_mov_b32 v[124:125], v[0:1], v[0:1]
	v_pk_mov_b32 v[126:127], v[0:1], v[0:1]
	s_waitcnt vmcnt(0)

; template <class Epi>
; __device__ __forceinline__ void gemm_phase(LAS unsigned char* lds, const Gemm g, const StaticOrder& S, const Epi& E) {
;     ...
;         const bool has_next = S.next(ui + 1, nxt);
;         const char* nA = has_next ? (const char*)g.A + (size_t)nxt.pm * tstepA : cA; const char* nB = has_next ? (const char*)g.Bt + (size_t)nxt.pn * tstepB : cB;
;     ...
;         for (int a = 0; a < 2; ++a)
; #pragma unroll
;             for (int b = 0; b < 2; ++b)
; #pragma unroll
;                 for (int m = 0; m < 4; ++m)
; #pragma unroll
;                     for (int n = 0; n < 2; ++n) acc[a][b][m][n] = (f32x4){0.f, 0.f, 0.f, 0.f};
;         cur = nxt; cA = nA; cB = nB; ++ui;
;     __device__ __forceinline__ void operator()(const Acc& acc, const Unit& u, int wr, int wc, int fr, int fq) const {
;         float ssv[2][4];
; #pragma unroll
;         for (int ai = 0; ai < 2; ++ai)
; #pragma unroll
;             for (int m = 0; m < 4; ++m) ssv[ai][m] = ss[u.pm * 256 + ai * 128 + wr * 64 + m * 16 + fr];
.LBB0_1731:
	s_ashr_i32 s21, s20, 31
	s_lshl_b64 s[22:23], s[20:21], 19
	s_add_u32 s22, s18, s22
	s_addc_u32 s23, s19, s23
	s_and_b64 s[24:25], s[6:7], exec
	s_cselect_b32 s21, s23, s27
	s_cselect_b32 s51, s22, s26
	s_ashr_i32 s15, s14, 31
	s_lshl_b64 s[24:25], s[14:15], 19
	v_readlane_b32 s30, v254, 43
	v_readlane_b32 s31, v254, 44
	s_add_u32 s24, s30, s24
	s_addc_u32 s25, s31, s25
	s_and_b64 s[30:31], s[6:7], exec
	s_cselect_b32 s15, s25, s29
	s_cselect_b32 s52, s24, s28
	s_add_u32 s26, s26, 0x40080
	s_addc_u32 s27, s27, 0
	s_add_u32 s53, s28, 0x100
	v_mov_b32_e32 v0, 0
	s_addc_u32 s54, s29, 0
	s_mov_b32 s55, -2
	v_mov_b32_e32 v1, 0
	v_pk_mov_b32 v[2:3], v[0:1], v[0:1]
	v_pk_mov_b32 v[4:5], v[0:1], v[0:1]
	v_pk_mov_b32 v[6:7], v[0:1], v[0:1]
	v_pk_mov_b32 v[8:9], v[0:1], v[0:1]
	v_pk_mov_b32 v[10:11], v[0:1], v[0:1]
	v_pk_mov_b32 v[12:13], v[0:1], v[0:1]
	v_pk_mov_b32 v[14:15], v[0:1], v[0:1]
	v_pk_mov_b32 v[16:17], v[0:1], v[0:1]
	v_pk_mov_b32 v[18:19], v[0:1], v[0:1]
	v_pk_mov_b32 v[20:21], v[0:1], v[0:1]
	v_pk_mov_b32 v[22:23], v[0:1], v[0:1]
	v_pk_mov_b32 v[24:25], v[0:1], v[0:1]
	v_pk_mov_b32 v[26:27], v[0:1], v[0:1]
	v_pk_mov_b32 v[28:29], v[0:1], v[0:1]
	v_pk_mov_b32 v[30:31], v[0:1], v[0:1]
	v_pk_mov_b32 v[32:33], v[0:1], v[0:1]
	v_pk_mov_b32 v[34:35], v[0:1], v[0:1]
	v_pk_mov_b32 v[36:37], v[0:1], v[0:1]
	v_pk_mov_b32 v[38:39], v[0:1], v[0:1]
	v_pk_mov_b32 v[40:41], v[0:1], v[0:1]
	v_pk_mov_b32 v[42:43], v[0:1], v[0:1]
	v_pk_mov_b32 v[44:45], v[0:1], v[0:1]
	v_pk_mov_b32 v[46:47], v[0:1], v[0:1]
	v_pk_mov_b32 v[48:49], v[0:1], v[0:1]
	v_pk_mov_b32 v[50:51], v[0:1], v[0:1]
	v_pk_mov_b32 v[52:53], v[0:1], v[0:1]
	v_pk_mov_b32 v[54:55], v[0:1], v[0:1]
	v_pk_mov_b32 v[56:57], v[0:1], v[0:1]
	v_pk_mov_b32 v[58:59], v[0:1], v[0:1]
	v_pk_mov_b32 v[60:61], v[0:1], v[0:1]
	v_pk_mov_b32 v[62:63], v[0:1], v[0:1]
	v_pk_mov_b32 v[64:65], v[0:1], v[0:1]
	v_pk_mov_b32 v[66:67], v[0:1], v[0:1]
	v_pk_mov_b32 v[68:69], v[0:1], v[0:1]
	v_pk_mov_b32 v[70:71], v[0:1], v[0:1]
	v_pk_mov_b32 v[72:73], v[0:1], v[0:1]
	v_pk_mov_b32 v[74:75], v[0:1], v[0:1]
	v_pk_mov_b32 v[76:77], v[0:1], v[0:1]
	v_pk_mov_b32 v[78:79], v[0:1], v[0:1]
	v_pk_mov_b32 v[80:81], v[0:1], v[0:1]
	v_pk_mov_b32 v[82:83], v[0:1], v[0:1]
	v_pk_mov_b32 v[84:85], v[0:1], v[0:1]
	v_pk_mov_b32 v[86:87], v[0:1], v[0:1]
	v_pk_mov_b32 v[88:89], v[0:1], v[0:1]
	v_pk_mov_b32 v[90:91], v[0:1], v[0:1]
	v_pk_mov_b32 v[92:93], v[0:1], v[0:1]
	v_pk_mov_b32 v[94:95], v[0:1], v[0:1]
	v_pk_mov_b32 v[96:97], v[0:1], v[0:1]
	v_pk_mov_b32 v[98:99], v[0:1], v[0:1]
	v_pk_mov_b32 v[100:101], v[0:1], v[0:1]
	v_pk_mov_b32 v[102:103], v[0:1], v[0:1]
	v_pk_mov_b32 v[104:105], v[0:1], v[0:1]
	v_pk_mov_b32 v[106:107], v[0:1], v[0:1]
	v_pk_mov_b32 v[108:109], v[0:1], v[0:1]
	v_pk_mov_b32 v[110:111], v[0:1], v[0:1]
	v_pk_mov_b32 v[112:113], v[0:1], v[0:1]
	v_pk_mov_b32 v[114:115], v[0:1], v[0:1]
	v_pk_mov_b32 v[116:117], v[0:1], v[0:1]
	v_pk_mov_b32 v[118:119], v[0:1], v[0:1]
	v_pk_mov_b32 v[120:121], v[0:1], v[0:1]
	v_pk_mov_b32 v[122:123], v[0:1], v[0:1]
	v_pk_mov_b32 v[124:125], v[0:1], v[0:1]
	v_pk_mov_b32 v[126:127], v[0:1], v[0:1]
	s_waitcnt vmcnt(0)
	s_lshl_b32 s85, s0, 8
	s_add_i32 s85, s85, s40
	v_or_b32_e32 v250, s85, v144
	v_ashrrev_i32_e32 v251, 31, v250
	v_lshl_add_u64 v[252:253], v[250:251], 2, s[16:17]
	global_load_dword v235, v[252:253], off
	global_load_dword v236, v[252:253], off offset:64
	global_load_dword v237, v[252:253], off offset:128
	global_load_dword v238, v[252:253], off offset:192
	global_load_dword v239, v[252:253], off offset:512
	global_load_dword v240, v[252:253], off offset:576
	global_load_dword v241, v[252:253], off offset:640
	global_load_dword v242, v[252:253], off offset:704

; template <class Epi>
; __device__ __forceinline__ void gemm_phase(LAS unsigned char* lds, const Gemm g, const StaticOrder& S, const Epi& E) {
;     ...
;         for (int a = 0; a < 2; ++a)
; #pragma unroll
;             for (int b = 0; b < 2; ++b)
; #pragma unroll
;                 for (int m = 0; m < 4; ++m)
; #pragma unroll
;                     for (int n = 0; n < 2; ++n) acc[a][b][m][n] = (f32x4){0.f, 0.f, 0.f, 0.f};
;         cur = nxt; cA = nA; cB = nB; ++ui;
.LBB0_1827:
	s_add_u32 s14, s6, 0x100
	s_addc_u32 s15, s7, 0
	s_add_u32 s2, s8, 0xc000
	v_mov_b32_e32 v0, 0
	s_addc_u32 s3, s9, 0
	s_mov_b32 s16, -2
	v_mov_b32_e32 v1, 0
	v_pk_mov_b32 v[2:3], v[0:1], v[0:1]
	v_pk_mov_b32 v[4:5], v[0:1], v[0:1]
	v_pk_mov_b32 v[6:7], v[0:1], v[0:1]
	v_pk_mov_b32 v[8:9], v[0:1], v[0:1]
	v_pk_mov_b32 v[10:11], v[0:1], v[0:1]
	v_pk_mov_b32 v[12:13], v[0:1], v[0:1]
	v_pk_mov_b32 v[14:15], v[0:1], v[0:1]
	v_pk_mov_b32 v[16:17], v[0:1], v[0:1]
	v_pk_mov_b32 v[18:19], v[0:1], v[0:1]
	v_pk_mov_b32 v[20:21], v[0:1], v[0:1]
	v_pk_mov_b32 v[22:23], v[0:1], v[0:1]
	v_pk_mov_b32 v[24:25], v[0:1], v[0:1]
	v_pk_mov_b32 v[26:27], v[0:1], v[0:1]
	v_pk_mov_b32 v[28:29], v[0:1], v[0:1]
	v_pk_mov_b32 v[30:31], v[0:1], v[0:1]
	v_pk_mov_b32 v[32:33], v[0:1], v[0:1]
	v_pk_mov_b32 v[34:35], v[0:1], v[0:1]
	v_pk_mov_b32 v[36:37], v[0:1], v[0:1]
	v_pk_mov_b32 v[38:39], v[0:1], v[0:1]
	v_pk_mov_b32 v[40:41], v[0:1], v[0:1]
	v_pk_mov_b32 v[42:43], v[0:1], v[0:1]
	v_pk_mov_b32 v[44:45], v[0:1], v[0:1]
	v_pk_mov_b32 v[46:47], v[0:1], v[0:1]
	v_pk_mov_b32 v[48:49], v[0:1], v[0:1]
	v_pk_mov_b32 v[50:51], v[0:1], v[0:1]
	v_pk_mov_b32 v[52:53], v[0:1], v[0:1]
	v_pk_mov_b32 v[54:55], v[0:1], v[0:1]
	v_pk_mov_b32 v[56:57], v[0:1], v[0:1]
	v_pk_mov_b32 v[58:59], v[0:1], v[0:1]
	v_pk_mov_b32 v[60:61], v[0:1], v[0:1]
	v_pk_mov_b32 v[62:63], v[0:1], v[0:1]
	v_pk_mov_b32 v[64:65], v[0:1], v[0:1]
	v_pk_mov_b32 v[66:67], v[0:1], v[0:1]
	v_pk_mov_b32 v[68:69], v[0:1], v[0:1]
	v_pk_mov_b32 v[70:71], v[0:1], v[0:1]
	v_pk_mov_b32 v[72:73], v[0:1], v[0:1]
	v_pk_mov_b32 v[74:75], v[0:1], v[0:1]
	v_pk_mov_b32 v[76:77], v[0:1], v[0:1]
	v_pk_mov_b32 v[78:79], v[0:1], v[0:1]
	v_pk_mov_b32 v[80:81], v[0:1], v[0:1]
	v_pk_mov_b32 v[82:83], v[0:1], v[0:1]
	v_pk_mov_b32 v[84:85], v[0:1], v[0:1]
	v_pk_mov_b32 v[86:87], v[0:1], v[0:1]
	v_pk_mov_b32 v[88:89], v[0:1], v[0:1]
	v_pk_mov_b32 v[90:91], v[0:1], v[0:1]
	v_pk_mov_b32 v[92:93], v[0:1], v[0:1]
	v_pk_mov_b32 v[94:95], v[0:1], v[0:1]
	v_pk_mov_b32 v[96:97], v[0:1], v[0:1]
	v_pk_mov_b32 v[98:99], v[0:1], v[0:1]
	v_pk_mov_b32 v[100:101], v[0:1], v[0:1]
	v_pk_mov_b32 v[102:103], v[0:1], v[0:1]
	v_pk_mov_b32 v[104:105], v[0:1], v[0:1]
	v_pk_mov_b32 v[106:107], v[0:1], v[0:1]
	v_pk_mov_b32 v[108:109], v[0:1], v[0:1]
	v_pk_mov_b32 v[110:111], v[0:1], v[0:1]
	v_pk_mov_b32 v[112:113], v[0:1], v[0:1]
	v_pk_mov_b32 v[114:115], v[0:1], v[0:1]
	v_pk_mov_b32 v[116:117], v[0:1], v[0:1]
	v_pk_mov_b32 v[118:119], v[0:1], v[0:1]
	v_pk_mov_b32 v[120:121], v[0:1], v[0:1]
	v_pk_mov_b32 v[122:123], v[0:1], v[0:1]
	v_pk_mov_b32 v[124:125], v[0:1], v[0:1]
	v_pk_mov_b32 v[126:127], v[0:1], v[0:1]
	s_waitcnt vmcnt(0)
